# ffn_conv walks its jobs (channel blocks) in descending order so the most recently produced gate/val columns are read first (Infinity Cache residency)
# speedup vs baseline: 1.0088x; 1.0028x over previous
;     __device__ __forceinline__ const char* a(const pg8::Unit& u) const { return (const char*)ws + aoff + (size_t)u.pm * 256 * K_ * 2 + (u.kq < 0 ? 0 : u.kq * (K_ / 4) * 2); }
;     __device__ __forceinline__ const char* b(const pg8::Unit& u) const { return (const char*)ws + boff + (size_t)u.pn * 256 * K_ * 2 + (u.kq < 0 ? 0 : u.kq * (K_ / 4) * 2); }
;     __device__ __forceinline__ const char* a(const pg8::Unit& u) const { return (const char*)ws + WS_A + (size_t)u.pm * 256 * D * 2; }
;     __device__ __forceinline__ const char* b(const pg8::Unit& u) const { return (const char*)ws + boff + (size_t)u.pn * 256 * D * 2; }
;     __device__ __forceinline__ const char* a(const pg8::Unit& u) const { return (const char*)ws + WS_A + (size_t)u.pm * 256 * D * 2; }
;     __device__ __forceinline__ const char* b(const pg8::Unit& u) const { return (const char*)ws + boff + (size_t)u.pn * 256 * D * 2; }
;     __device__ __forceinline__ const char* a(const pg8::Unit& u) const { return (const char*)ws + WS_W1 + (size_t)(u.pm & 1) * 256 * 256 * 2; }
;     __device__ __forceinline__ const char* b(const pg8::Unit& u) const { return (const char*)ws + WS_A + ((size_t)u.pn * 256 * D + (size_t)(u.pm >> 1) * 256) * 2; }
;     __device__ __forceinline__ const char* a(const pg8::Unit& u) const { return (const char*)ws + (u.pm < 64 ? WS_W2 : WS_W2C); }
; __device__ __forceinline__ void ffn_conv_phase(Frame& F, int L, int nrows, bool probe_alt = false) {
;     ...
;         FFN_LOAD_ROW(0); FFN_LOAD_ROW(1);
;         f32x2 acc[8][4];
;         { const f32x4* p = (const f32x4*)(cb_ + c0); const f32x4 a = p[0], b = p[1];
; #pragma unroll
;           for (int i = 0; i < 8; ++i) { acc[i][0] = (f32x2){a.x, a.y}; acc[i][1] = (f32x2){a.z, a.w}; acc[i][2] = (f32x2){b.x, b.y}; acc[i][3] = (f32x2){b.z, b.w}; } }
;         FFN_ACC_ROW(0);
;         FFN_LOAD_ROW(2);
; #pragma unroll
;         for (int i = 0; i < 8; ++i) rv[i] = __builtin_nontemporal_load((const u32x4*)(val + (size_t)(rb + tq * 8 + i) * DFF + c0));
;         FFN_ACC_ROW(1);
;         FFN_ACC_ROW(2);
.LBB0_1205:
	s_or_b64 exec, exec, s[4:5]
	s_waitcnt vmcnt(8)
	v_lshlrev_b32_e32 v156, 16, v12
	v_and_b32_e32 v157, 0xffff0000, v12
	v_lshlrev_b32_e32 v12, 16, v13
	v_and_b32_e32 v13, 0xffff0000, v13
	v_lshlrev_b32_e32 v160, 16, v20
	v_and_b32_e32 v161, 0xffff0000, v20
	v_lshlrev_b32_e32 v20, 16, v21
	v_and_b32_e32 v21, 0xffff0000, v21
	s_waitcnt vmcnt(4)
	v_pk_fma_f32 v[12:13], v[134:135], v[12:13], v[130:131]
	v_lshlrev_b32_e32 v158, 16, v14
	v_and_b32_e32 v159, 0xffff0000, v14
	v_lshlrev_b32_e32 v164, 16, v0
	v_and_b32_e32 v165, 0xffff0000, v0
	v_lshlrev_b32_e32 v0, 16, v1
	v_and_b32_e32 v1, 0xffff0000, v1
	s_waitcnt vmcnt(3)
	v_pk_fma_f32 v[12:13], v[142:143], v[20:21], v[12:13]
	v_lshlrev_b32_e32 v162, 16, v22
	v_and_b32_e32 v163, 0xffff0000, v22
	s_waitcnt vmcnt(1)
	v_pk_fma_f32 v[172:173], v[150:151], v[0:1], v[12:13]
	v_pk_fma_f32 v[12:13], v[124:125], v[158:159], v[120:121]
	v_lshlrev_b32_e32 v14, 16, v15
	v_and_b32_e32 v15, 0xffff0000, v15
	v_lshlrev_b32_e32 v168, 16, v2
	v_and_b32_e32 v169, 0xffff0000, v2
	v_pk_fma_f32 v[12:13], v[136:137], v[162:163], v[12:13]
	v_pk_fma_f32 v[20:21], v[134:135], v[20:21], v[130:131]
	v_lshlrev_b32_e32 v22, 16, v23
	v_and_b32_e32 v23, 0xffff0000, v23
	s_waitcnt vmcnt(0)
	v_pk_fma_f32 v[174:175], v[144:145], v[168:169], v[12:13]
	v_pk_fma_f32 v[12:13], v[126:127], v[14:15], v[122:123]
	v_lshlrev_b32_e32 v14, 16, v29
	v_and_b32_e32 v15, 0xffff0000, v29
	v_pk_fma_f32 v[20:21], v[142:143], v[0:1], v[20:21]
	v_lshlrev_b32_e32 v2, 16, v3
	v_and_b32_e32 v3, 0xffff0000, v3
	v_pk_fma_f32 v[156:157], v[132:133], v[156:157], v[128:129]
	v_pk_fma_f32 v[12:13], v[138:139], v[22:23], v[12:13]
	v_pk_fma_f32 v[158:159], v[150:151], v[14:15], v[20:21]
	v_pk_fma_f32 v[20:21], v[124:125], v[162:163], v[120:121]
	v_pk_fma_f32 v[156:157], v[140:141], v[160:161], v[156:157]
	v_pk_fma_f32 v[180:181], v[146:147], v[2:3], v[12:13]
	v_lshlrev_b32_e32 v12, 16, v28
	v_and_b32_e32 v13, 0xffff0000, v28
	v_lshlrev_b32_e32 v28, 16, v30
	v_and_b32_e32 v29, 0xffff0000, v30
	v_pk_fma_f32 v[20:21], v[136:137], v[168:169], v[20:21]
	v_pk_fma_f32 v[170:171], v[148:149], v[164:165], v[156:157]
	v_pk_fma_f32 v[156:157], v[132:133], v[160:161], v[128:129]
	v_pk_fma_f32 v[160:161], v[144:145], v[28:29], v[20:21]
	v_pk_fma_f32 v[20:21], v[126:127], v[22:23], v[122:123]
	v_lshlrev_b32_e32 v30, 16, v31
	v_and_b32_e32 v31, 0xffff0000, v31
	v_pk_fma_f32 v[20:21], v[138:139], v[2:3], v[20:21]
	v_pk_fma_f32 v[0:1], v[134:135], v[0:1], v[130:131]
	v_pk_fma_f32 v[162:163], v[146:147], v[30:31], v[20:21]
	v_lshlrev_b32_e32 v20, 16, v4
	v_and_b32_e32 v21, 0xffff0000, v4
	v_lshlrev_b32_e32 v4, 16, v5
	v_and_b32_e32 v5, 0xffff0000, v5
	v_pk_fma_f32 v[0:1], v[142:143], v[14:15], v[0:1]
	v_lshlrev_b32_e32 v22, 16, v6
	v_pk_fma_f32 v[166:167], v[150:151], v[4:5], v[0:1]
	v_pk_fma_f32 v[0:1], v[124:125], v[168:169], v[120:121]
	v_and_b32_e32 v23, 0xffff0000, v6
	v_pk_fma_f32 v[0:1], v[136:137], v[28:29], v[0:1]
	v_pk_fma_f32 v[156:157], v[140:141], v[164:165], v[156:157]
	v_pk_fma_f32 v[164:165], v[132:133], v[164:165], v[128:129]
	v_pk_fma_f32 v[168:169], v[144:145], v[22:23], v[0:1]
	v_pk_fma_f32 v[0:1], v[126:127], v[2:3], v[122:123]
	v_pk_fma_f32 v[156:157], v[148:149], v[12:13], v[156:157]
	v_lshlrev_b32_e32 v6, 16, v7
	v_and_b32_e32 v7, 0xffff0000, v7
	v_pk_fma_f32 v[164:165], v[140:141], v[12:13], v[164:165]
	v_pk_fma_f32 v[0:1], v[138:139], v[30:31], v[0:1]
	v_pk_fma_f32 v[12:13], v[132:133], v[12:13], v[128:129]
	v_pk_fma_f32 v[188:189], v[146:147], v[6:7], v[0:1]
	v_lshlrev_b32_e32 v0, 16, v68
	v_and_b32_e32 v1, 0xffff0000, v68
	v_pk_fma_f32 v[12:13], v[140:141], v[20:21], v[12:13]
	v_lshlrev_b32_e32 v2, 16, v69
	v_pk_fma_f32 v[190:191], v[148:149], v[0:1], v[12:13]
	v_pk_fma_f32 v[12:13], v[134:135], v[14:15], v[130:131]
	v_and_b32_e32 v3, 0xffff0000, v69
	v_pk_fma_f32 v[12:13], v[142:143], v[4:5], v[12:13]
	v_lshlrev_b32_e32 v68, 16, v70
	v_pk_fma_f32 v[192:193], v[150:151], v[2:3], v[12:13]
	v_pk_fma_f32 v[12:13], v[124:125], v[28:29], v[120:121]
	v_and_b32_e32 v69, 0xffff0000, v70
	v_pk_fma_f32 v[12:13], v[136:137], v[22:23], v[12:13]
	v_lshlrev_b32_e32 v70, 16, v71
	v_pk_fma_f32 v[194:195], v[144:145], v[68:69], v[12:13]
	v_pk_fma_f32 v[12:13], v[126:127], v[30:31], v[122:123]
	v_and_b32_e32 v71, 0xffff0000, v71
	v_pk_fma_f32 v[12:13], v[138:139], v[6:7], v[12:13]
	v_pk_fma_f32 v[4:5], v[134:135], v[4:5], v[130:131]
	v_pk_fma_f32 v[196:197], v[146:147], v[70:71], v[12:13]
	v_lshlrev_b32_e32 v12, 16, v8
	v_and_b32_e32 v13, 0xffff0000, v8
	v_lshlrev_b32_e32 v8, 16, v9
	v_and_b32_e32 v9, 0xffff0000, v9
	v_pk_fma_f32 v[4:5], v[142:143], v[2:3], v[4:5]
	v_lshlrev_b32_e32 v14, 16, v10
	v_pk_fma_f32 v[200:201], v[150:151], v[8:9], v[4:5]
	v_pk_fma_f32 v[4:5], v[124:125], v[22:23], v[120:121]
	v_and_b32_e32 v15, 0xffff0000, v10
	v_pk_fma_f32 v[4:5], v[136:137], v[68:69], v[4:5]
	v_pk_fma_f32 v[164:165], v[148:149], v[20:21], v[164:165]
	v_pk_fma_f32 v[20:21], v[132:133], v[20:21], v[128:129]
	v_pk_fma_f32 v[202:203], v[144:145], v[14:15], v[4:5]
	v_pk_fma_f32 v[4:5], v[126:127], v[6:7], v[122:123]
	v_lshlrev_b32_e32 v10, 16, v11
	v_and_b32_e32 v11, 0xffff0000, v11
	v_pk_fma_f32 v[20:21], v[140:141], v[0:1], v[20:21]
	v_pk_fma_f32 v[4:5], v[138:139], v[70:71], v[4:5]
	v_pk_fma_f32 v[0:1], v[132:133], v[0:1], v[128:129]
	v_pk_fma_f32 v[212:213], v[146:147], v[10:11], v[4:5]
	v_lshlrev_b32_e32 v4, 16, v112
	v_and_b32_e32 v5, 0xffff0000, v112
	v_pk_fma_f32 v[0:1], v[140:141], v[12:13], v[0:1]
	v_lshlrev_b32_e32 v6, 16, v113
	v_pk_fma_f32 v[214:215], v[148:149], v[4:5], v[0:1]
	v_pk_fma_f32 v[0:1], v[134:135], v[2:3], v[130:131]
;     __device__ __forceinline__ const char* a(const pg8::Unit& u) const { return (const char*)ws + aoff + (size_t)u.pm * 256 * K_ * 2 + (u.kq < 0 ? 0 : u.kq * (K_ / 4) * 2); }
;     __device__ __forceinline__ const char* b(const pg8::Unit& u) const { return (const char*)ws + boff + (size_t)u.pn * 256 * K_ * 2 + (u.kq < 0 ? 0 : u.kq * (K_ / 4) * 2); }
;     __device__ __forceinline__ const char* a(const pg8::Unit& u) const { return (const char*)ws + WS_A + (size_t)u.pm * 256 * D * 2; }
;     __device__ __forceinline__ const char* b(const pg8::Unit& u) const { return (const char*)ws + boff + (size_t)u.pn * 256 * D * 2; }
;     __device__ __forceinline__ const char* a(const pg8::Unit& u) const { return (const char*)ws + WS_A + (size_t)u.pm * 256 * D * 2; }
;     __device__ __forceinline__ const char* b(const pg8::Unit& u) const { return (const char*)ws + boff + (size_t)u.pn * 256 * D * 2; }
;     __device__ __forceinline__ const char* a(const pg8::Unit& u) const { return (const char*)ws + WS_W1 + (size_t)(u.pm & 1) * 256 * 256 * 2; }
;     __device__ __forceinline__ const char* b(const pg8::Unit& u) const { return (const char*)ws + WS_A + ((size_t)u.pn * 256 * D + (size_t)(u.pm >> 1) * 256) * 2; }
;     __device__ __forceinline__ const char* a(const pg8::Unit& u) const { return (const char*)ws + (u.pm < 64 ? WS_W2 : WS_W2C); }
; __device__ __forceinline__ void ffn_conv_phase(Frame& F, int L, int nrows, bool probe_alt = false) {
;     ...
;         FFN_LOAD_ROW(0); FFN_LOAD_ROW(1);
;         f32x2 acc[8][4];
;         { const f32x4* p = (const f32x4*)(cb_ + c0); const f32x4 a = p[0], b = p[1];
; #pragma unroll
;           for (int i = 0; i < 8; ++i) { acc[i][0] = (f32x2){a.x, a.y}; acc[i][1] = (f32x2){a.z, a.w}; acc[i][2] = (f32x2){b.x, b.y}; acc[i][3] = (f32x2){b.z, b.w}; } }
;         FFN_ACC_ROW(0);
;         FFN_LOAD_ROW(2);
; #pragma unroll
;         for (int i = 0; i < 8; ++i) rv[i] = __builtin_nontemporal_load((const u32x4*)(val + (size_t)(rb + tq * 8 + i) * DFF + c0));
;         FFN_ACC_ROW(1);
;         FFN_ACC_ROW(2);
	v_and_b32_e32 v7, 0xffff0000, v113
	v_pk_fma_f32 v[0:1], v[142:143], v[8:9], v[0:1]
	v_pk_fma_f32 v[198:199], v[148:149], v[12:13], v[20:21]
	v_pk_fma_f32 v[216:217], v[150:151], v[6:7], v[0:1]
	v_pk_fma_f32 v[0:1], v[124:125], v[68:69], v[120:121]
	v_lshlrev_b32_e32 v20, 16, v114
	v_and_b32_e32 v21, 0xffff0000, v114
	v_pk_fma_f32 v[0:1], v[136:137], v[14:15], v[0:1]
	v_pk_fma_f32 v[8:9], v[134:135], v[8:9], v[130:131]
	v_pk_fma_f32 v[218:219], v[144:145], v[20:21], v[0:1]
	v_pk_fma_f32 v[0:1], v[126:127], v[70:71], v[122:123]
	v_lshlrev_b32_e32 v2, 16, v17
	v_and_b32_e32 v3, 0xffff0000, v17
	v_pk_fma_f32 v[8:9], v[142:143], v[6:7], v[8:9]
	v_lshlrev_b32_e32 v22, 16, v115
	v_and_b32_e32 v23, 0xffff0000, v115
	v_pk_fma_f32 v[0:1], v[138:139], v[10:11], v[0:1]
	v_pk_fma_f32 v[224:225], v[150:151], v[2:3], v[8:9]
	v_pk_fma_f32 v[8:9], v[124:125], v[14:15], v[120:121]
	v_pk_fma_f32 v[220:221], v[146:147], v[22:23], v[0:1]
	v_lshlrev_b32_e32 v0, 16, v16
	v_and_b32_e32 v1, 0xffff0000, v16
	v_lshlrev_b32_e32 v16, 16, v18
	v_and_b32_e32 v17, 0xffff0000, v18
	v_pk_fma_f32 v[8:9], v[136:137], v[20:21], v[8:9]
	v_pk_fma_f32 v[12:13], v[132:133], v[12:13], v[128:129]
	v_pk_fma_f32 v[226:227], v[144:145], v[16:17], v[8:9]
	v_pk_fma_f32 v[8:9], v[126:127], v[10:11], v[122:123]
	v_lshlrev_b32_e32 v18, 16, v19
	v_and_b32_e32 v19, 0xffff0000, v19
	v_pk_fma_f32 v[12:13], v[140:141], v[4:5], v[12:13]
	v_pk_fma_f32 v[8:9], v[138:139], v[22:23], v[8:9]
	v_pk_fma_f32 v[4:5], v[132:133], v[4:5], v[128:129]
	v_pk_fma_f32 v[222:223], v[148:149], v[0:1], v[12:13]
	v_pk_fma_f32 v[228:229], v[146:147], v[18:19], v[8:9]
	v_lshlrev_b32_e32 v8, 16, v116
	v_and_b32_e32 v9, 0xffff0000, v116
	v_pk_fma_f32 v[0:1], v[140:141], v[0:1], v[4:5]
	v_lshlrev_b32_e32 v10, 16, v117
	v_pk_fma_f32 v[230:231], v[148:149], v[8:9], v[0:1]
	v_pk_fma_f32 v[0:1], v[134:135], v[6:7], v[130:131]
	v_and_b32_e32 v11, 0xffff0000, v117
	v_pk_fma_f32 v[0:1], v[142:143], v[2:3], v[0:1]
	v_lshlrev_b32_e32 v12, 16, v118
	v_pk_fma_f32 v[232:233], v[150:151], v[10:11], v[0:1]
	v_pk_fma_f32 v[0:1], v[124:125], v[20:21], v[120:121]
	v_and_b32_e32 v13, 0xffff0000, v118
	v_pk_fma_f32 v[0:1], v[136:137], v[16:17], v[0:1]
	v_lshlrev_b32_e32 v14, 16, v119
	v_pk_fma_f32 v[234:235], v[144:145], v[12:13], v[0:1]
	v_pk_fma_f32 v[0:1], v[126:127], v[22:23], v[122:123]
	v_and_b32_e32 v15, 0xffff0000, v119
	v_pk_fma_f32 v[0:1], v[138:139], v[18:19], v[0:1]
	s_mul_i32 s4, s26, s78
	v_pk_fma_f32 v[236:237], v[146:147], v[14:15], v[0:1]
	v_subrev_u32_e32 v0, s4, v176
	v_readlane_b32 s4, v253, 46
	v_add_u32_e32 v2, s101, v0
	v_readlane_b32 s5, v253, 47
	v_add_u32_e32 v3, -7, v2
	v_lshl_add_u64 v[116:117], s[30:31], 0, v[152:153]
	v_lshl_add_u64 v[0:1], v[154:155], 1, s[4:5]
	v_mad_i64_i32 v[150:151], s[4:5], v3, s89, v[0:1]
	v_add_u32_e32 v3, -6, v2
	v_mad_i64_i32 v[148:149], s[4:5], v3, s89, v[0:1]
	v_add_u32_e32 v3, -5, v2
	v_mad_i64_i32 v[146:147], s[4:5], v3, s89, v[0:1]
	v_add_u32_e32 v3, -4, v2
	v_mad_i64_i32 v[144:145], s[4:5], v3, s89, v[0:1]
	v_add_u32_e32 v3, -3, v2
	v_mad_i64_i32 v[142:143], s[4:5], v3, s89, v[0:1]
	v_add_u32_e32 v3, -2, v2
	v_mad_i64_i32 v[140:141], s[4:5], v3, s89, v[0:1]
	v_add_u32_e32 v3, -1, v2
	v_mad_i64_i32 v[138:139], s[4:5], v3, s89, v[0:1]
	v_mad_i64_i32 v[136:137], s[4:5], v2, s89, v[0:1]
	global_load_dwordx4 v[68:71], v[150:151], off nt
	global_load_dwordx4 v[28:31], v[148:149], off nt
	global_load_dwordx4 v[20:23], v[146:147], off nt
	global_load_dwordx4 v[16:19], v[144:145], off nt
	global_load_dwordx4 v[12:15], v[142:143], off nt
	global_load_dwordx4 v[8:11], v[140:141], off nt
	global_load_dwordx4 v[4:7], v[138:139], off nt
	global_load_dwordx4 v[0:3], v[136:137], off nt
	global_load_dwordx4 v[112:115], v[116:117], off offset:16
	global_load_dwordx4 v[120:123], v[116:117], off
	v_lshl_add_u64 v[124:125], s[34:35], 0, v[152:153]
	global_load_dwordx4 v[116:119], v[124:125], off offset:16
	global_load_dwordx4 v[128:131], v[124:125], off
	v_lshl_add_u64 v[132:133], s[44:45], 0, v[152:153]
	global_load_dwordx4 v[124:127], v[132:133], off offset:16
	s_nop 0
	global_load_dwordx4 v[132:135], v[132:133], off
	v_lshlrev_b32_e32 v154, 16, v72
	v_and_b32_e32 v155, 0xffff0000, v72
	v_lshlrev_b32_e32 v72, 16, v73
	v_and_b32_e32 v73, 0xffff0000, v73
	v_lshlrev_b32_e32 v184, 16, v92
	v_and_b32_e32 v185, 0xffff0000, v92
	v_lshlrev_b32_e32 v92, 16, v93
	v_and_b32_e32 v93, 0xffff0000, v93
	v_lshlrev_b32_e32 v182, 16, v74
	v_and_b32_e32 v183, 0xffff0000, v74
	v_lshlrev_b32_e32 v246, 16, v88
	v_and_b32_e32 v247, 0xffff0000, v88
	v_lshlrev_b32_e32 v88, 16, v89
	v_and_b32_e32 v89, 0xffff0000, v89
	v_lshlrev_b32_e32 v186, 16, v94
	v_and_b32_e32 v187, 0xffff0000, v94
	v_lshlrev_b32_e32 v74, 16, v75
	v_and_b32_e32 v75, 0xffff0000, v75
	v_lshlrev_b32_e32 v248, 16, v90
	v_and_b32_e32 v249, 0xffff0000, v90
	v_lshlrev_b32_e32 v94, 16, v95
	v_and_b32_e32 v95, 0xffff0000, v95
	v_lshlrev_b32_e32 v90, 16, v91
	v_and_b32_e32 v91, 0xffff0000, v91
	v_readlane_b32 s4, v255, 28
	s_add_i32 s77, s77, s4
	s_add_i32 s72, s72, s74
	s_cmp_lt_i32 s77, s7
	v_readlane_b32 s5, v255, 29
	s_waitcnt vmcnt(4)
	v_pk_fma_f32 v[72:73], v[122:123], v[72:73], v[172:173]
	v_pk_fma_f32 v[154:155], v[120:121], v[154:155], v[170:171]
	s_waitcnt vmcnt(2)
	v_pk_fma_f32 v[72:73], v[130:131], v[92:93], v[72:73]
	v_pk_fma_f32 v[92:93], v[122:123], v[92:93], v[158:159]
	s_waitcnt vmcnt(0)
	v_pk_fma_f32 v[206:207], v[134:135], v[88:89], v[72:73]
	v_pk_fma_f32 v[72:73], v[112:113], v[182:183], v[174:175]
	v_pk_fma_f32 v[92:93], v[130:131], v[88:89], v[92:93]
	v_pk_fma_f32 v[72:73], v[116:117], v[186:187], v[72:73]
	v_pk_fma_f32 v[88:89], v[122:123], v[88:89], v[166:167]
	v_pk_fma_f32 v[208:209], v[124:125], v[248:249], v[72:73]
	v_pk_fma_f32 v[72:73], v[114:115], v[74:75], v[180:181]
	v_lshlrev_b32_e32 v74, 16, v105
	v_and_b32_e32 v75, 0xffff0000, v105
	v_pk_fma_f32 v[72:73], v[118:119], v[94:95], v[72:73]
	v_pk_fma_f32 v[172:173], v[134:135], v[74:75], v[92:93]
	v_pk_fma_f32 v[92:93], v[112:113], v[186:187], v[160:161]
	v_pk_fma_f32 v[210:211], v[126:127], v[90:91], v[72:73]
	v_lshlrev_b32_e32 v72, 16, v104
	v_and_b32_e32 v73, 0xffff0000, v104
	v_lshlrev_b32_e32 v104, 16, v106
	v_and_b32_e32 v105, 0xffff0000, v106
	v_pk_fma_f32 v[92:93], v[116:117], v[248:249], v[92:93]
	v_lshlrev_b32_e32 v106, 16, v107
	v_pk_fma_f32 v[174:175], v[124:125], v[104:105], v[92:93]
	v_pk_fma_f32 v[92:93], v[114:115], v[94:95], v[162:163]
	v_and_b32_e32 v107, 0xffff0000, v107
	v_pk_fma_f32 v[92:93], v[118:119], v[90:91], v[92:93]
	v_pk_fma_f32 v[154:155], v[128:129], v[184:185], v[154:155]
	v_pk_fma_f32 v[180:181], v[126:127], v[106:107], v[92:93]
	v_lshlrev_b32_e32 v92, 16, v80
	v_and_b32_e32 v93, 0xffff0000, v80
	v_lshlrev_b32_e32 v80, 16, v81
	v_and_b32_e32 v81, 0xffff0000, v81
	v_pk_fma_f32 v[88:89], v[130:131], v[74:75], v[88:89]
	v_pk_fma_f32 v[204:205], v[132:133], v[246:247], v[154:155]
	v_pk_fma_f32 v[154:155], v[120:121], v[184:185], v[156:157]
	v_pk_fma_f32 v[184:185], v[134:135], v[80:81], v[88:89]
	v_pk_fma_f32 v[88:89], v[112:113], v[248:249], v[168:169]
	v_pk_fma_f32 v[154:155], v[128:129], v[246:247], v[154:155]
	v_lshlrev_b32_e32 v94, 16, v82
	v_and_b32_e32 v95, 0xffff0000, v82
	v_pk_fma_f32 v[88:89], v[116:117], v[104:105], v[88:89]
	v_pk_fma_f32 v[170:171], v[132:133], v[72:73], v[154:155]
	v_pk_fma_f32 v[154:155], v[120:121], v[246:247], v[164:165]
	v_pk_fma_f32 v[186:187], v[124:125], v[94:95], v[88:89]
	v_pk_fma_f32 v[88:89], v[114:115], v[90:91], v[188:189]
	v_lshlrev_b32_e32 v82, 16, v83
	v_and_b32_e32 v83, 0xffff0000, v83
	v_pk_fma_f32 v[154:155], v[128:129], v[72:73], v[154:155]
	v_pk_fma_f32 v[88:89], v[118:119], v[106:107], v[88:89]
	v_pk_fma_f32 v[72:73], v[120:121], v[72:73], v[190:191]
	v_pk_fma_f32 v[188:189], v[126:127], v[82:83], v[88:89]
	v_lshlrev_b32_e32 v88, 16, v100
	v_and_b32_e32 v89, 0xffff0000, v100
	v_pk_fma_f32 v[72:73], v[128:129], v[92:93], v[72:73]
	v_lshlrev_b32_e32 v90, 16, v101
	v_and_b32_e32 v91, 0xffff0000, v101
	v_pk_fma_f32 v[100:101], v[132:133], v[88:89], v[72:73]
	v_pk_fma_f32 v[72:73], v[122:123], v[74:75], v[192:193]
	v_pk_fma_f32 v[182:183], v[132:133], v[92:93], v[154:155]
	v_pk_fma_f32 v[72:73], v[130:131], v[80:81], v[72:73]
	v_lshlrev_b32_e32 v154, 16, v102
	v_pk_fma_f32 v[190:191], v[134:135], v[90:91], v[72:73]
	v_pk_fma_f32 v[72:73], v[112:113], v[104:105], v[194:195]
	v_and_b32_e32 v155, 0xffff0000, v102
	v_pk_fma_f32 v[72:73], v[116:117], v[94:95], v[72:73]
	v_pk_fma_f32 v[80:81], v[122:123], v[80:81], v[200:201]
	v_pk_fma_f32 v[192:193], v[124:125], v[154:155], v[72:73]
	v_pk_fma_f32 v[72:73], v[114:115], v[106:107], v[196:197]
	v_lshlrev_b32_e32 v74, 16, v77
	v_and_b32_e32 v75, 0xffff0000, v77
	v_pk_fma_f32 v[80:81], v[130:131], v[90:91], v[80:81]
	v_lshlrev_b32_e32 v102, 16, v103
	v_and_b32_e32 v103, 0xffff0000, v103
	v_pk_fma_f32 v[72:73], v[118:119], v[82:83], v[72:73]
	v_pk_fma_f32 v[92:93], v[120:121], v[92:93], v[198:199]
	v_pk_fma_f32 v[198:199], v[134:135], v[74:75], v[80:81]
	v_pk_fma_f32 v[80:81], v[112:113], v[94:95], v[202:203]
	v_pk_fma_f32 v[194:195], v[126:127], v[102:103], v[72:73]
	v_lshlrev_b32_e32 v72, 16, v76
	v_and_b32_e32 v73, 0xffff0000, v76
	v_lshlrev_b32_e32 v76, 16, v78
	v_and_b32_e32 v77, 0xffff0000, v78
	v_pk_fma_f32 v[80:81], v[116:117], v[154:155], v[80:81]
	v_lshlrev_b32_e32 v78, 16, v79
	v_pk_fma_f32 v[200:201], v[124:125], v[76:77], v[80:81]
	v_pk_fma_f32 v[80:81], v[114:115], v[82:83], v[212:213]
	v_and_b32_e32 v79, 0xffff0000, v79
	v_pk_fma_f32 v[92:93], v[128:129], v[88:89], v[92:93]
	v_pk_fma_f32 v[80:81], v[118:119], v[102:103], v[80:81]
	v_pk_fma_f32 v[88:89], v[120:121], v[88:89], v[214:215]
	v_pk_fma_f32 v[202:203], v[126:127], v[78:79], v[80:81]
	v_lshlrev_b32_e32 v80, 16, v96
	v_and_b32_e32 v81, 0xffff0000, v96
	v_pk_fma_f32 v[88:89], v[128:129], v[72:73], v[88:89]
	v_lshlrev_b32_e32 v82, 16, v97
	v_pk_fma_f32 v[168:169], v[132:133], v[80:81], v[88:89]
	v_pk_fma_f32 v[88:89], v[122:123], v[90:91], v[216:217]
	v_and_b32_e32 v83, 0xffff0000, v97
	v_pk_fma_f32 v[88:89], v[130:131], v[74:75], v[88:89]
	v_pk_fma_f32 v[196:197], v[132:133], v[72:73], v[92:93]
	v_pk_fma_f32 v[166:167], v[134:135], v[82:83], v[88:89]
	v_pk_fma_f32 v[88:89], v[112:113], v[154:155], v[218:219]
	v_lshlrev_b32_e32 v92, 16, v98
	v_and_b32_e32 v93, 0xffff0000, v98
	v_pk_fma_f32 v[88:89], v[116:117], v[76:77], v[88:89]
	v_lshlrev_b32_e32 v94, 16, v99
	v_pk_fma_f32 v[164:165], v[124:125], v[92:93], v[88:89]
	v_pk_fma_f32 v[88:89], v[114:115], v[102:103], v[220:221]
	v_and_b32_e32 v95, 0xffff0000, v99
	v_pk_fma_f32 v[88:89], v[118:119], v[78:79], v[88:89]
	v_pk_fma_f32 v[72:73], v[120:121], v[72:73], v[222:223]
	v_pk_fma_f32 v[162:163], v[126:127], v[94:95], v[88:89]
	v_lshlrev_b32_e32 v88, 16, v84
	v_and_b32_e32 v89, 0xffff0000, v84
	v_pk_fma_f32 v[72:73], v[128:129], v[80:81], v[72:73]
	v_lshlrev_b32_e32 v84, 16, v85
	v_pk_fma_f32 v[160:161], v[132:133], v[88:89], v[72:73]
	v_pk_fma_f32 v[72:73], v[122:123], v[74:75], v[224:225]
	v_and_b32_e32 v85, 0xffff0000, v85
;     __device__ __forceinline__ const char* a(const pg8::Unit& u) const { return (const char*)ws + aoff + (size_t)u.pm * 256 * K_ * 2 + (u.kq < 0 ? 0 : u.kq * (K_ / 4) * 2); }
;     __device__ __forceinline__ const char* b(const pg8::Unit& u) const { return (const char*)ws + boff + (size_t)u.pn * 256 * K_ * 2 + (u.kq < 0 ? 0 : u.kq * (K_ / 4) * 2); }
;     __device__ __forceinline__ const char* a(const pg8::Unit& u) const { return (const char*)ws + WS_A + (size_t)u.pm * 256 * D * 2; }
;     __device__ __forceinline__ const char* b(const pg8::Unit& u) const { return (const char*)ws + boff + (size_t)u.pn * 256 * D * 2; }
;     __device__ __forceinline__ const char* a(const pg8::Unit& u) const { return (const char*)ws + WS_A + (size_t)u.pm * 256 * D * 2; }
;     __device__ __forceinline__ const char* b(const pg8::Unit& u) const { return (const char*)ws + boff + (size_t)u.pn * 256 * D * 2; }
;     __device__ __forceinline__ const char* a(const pg8::Unit& u) const { return (const char*)ws + WS_W1 + (size_t)(u.pm & 1) * 256 * 256 * 2; }
;     __device__ __forceinline__ const char* b(const pg8::Unit& u) const { return (const char*)ws + WS_A + ((size_t)u.pn * 256 * D + (size_t)(u.pm >> 1) * 256) * 2; }
;     __device__ __forceinline__ const char* a(const pg8::Unit& u) const { return (const char*)ws + (u.pm < 64 ? WS_W2 : WS_W2C); }
; __device__ __forceinline__ void ffn_conv_phase(Frame& F, int L, int nrows, bool probe_alt = false) {
;     ...
;         FFN_LOAD_ROW(0); FFN_LOAD_ROW(1);
;         f32x2 acc[8][4];
;         { const f32x4* p = (const f32x4*)(cb_ + c0); const f32x4 a = p[0], b = p[1];
; #pragma unroll
;           for (int i = 0; i < 8; ++i) { acc[i][0] = (f32x2){a.x, a.y}; acc[i][1] = (f32x2){a.z, a.w}; acc[i][2] = (f32x2){b.x, b.y}; acc[i][3] = (f32x2){b.z, b.w}; } }
;         FFN_ACC_ROW(0);
;         FFN_LOAD_ROW(2);
; #pragma unroll
;         for (int i = 0; i < 8; ++i) rv[i] = __builtin_nontemporal_load((const u32x4*)(val + (size_t)(rb + tq * 8 + i) * DFF + c0));
;         FFN_ACC_ROW(1);
	v_pk_fma_f32 v[72:73], v[130:131], v[82:83], v[72:73]
	v_lshlrev_b32_e32 v90, 16, v86
	v_pk_fma_f32 v[158:159], v[134:135], v[84:85], v[72:73]
	v_pk_fma_f32 v[72:73], v[112:113], v[76:77], v[226:227]
	v_and_b32_e32 v91, 0xffff0000, v86
	v_pk_fma_f32 v[72:73], v[116:117], v[92:93], v[72:73]
	v_lshlrev_b32_e32 v86, 16, v87
	v_pk_fma_f32 v[156:157], v[124:125], v[90:91], v[72:73]
	v_pk_fma_f32 v[72:73], v[114:115], v[78:79], v[228:229]
	v_and_b32_e32 v87, 0xffff0000, v87
	v_pk_fma_f32 v[72:73], v[118:119], v[94:95], v[72:73]
	v_pk_fma_f32 v[80:81], v[120:121], v[80:81], v[230:231]
	v_pk_fma_f32 v[154:155], v[126:127], v[86:87], v[72:73]
	v_lshlrev_b32_e32 v72, 16, v108
	v_and_b32_e32 v73, 0xffff0000, v108
	v_pk_fma_f32 v[80:81], v[128:129], v[88:89], v[80:81]
	v_lshlrev_b32_e32 v76, 16, v110
	v_and_b32_e32 v77, 0xffff0000, v110
	v_lshlrev_b32_e32 v78, 16, v111
	v_and_b32_e32 v79, 0xffff0000, v111
	v_pk_fma_f32 v[110:111], v[132:133], v[72:73], v[80:81]
	v_pk_fma_f32 v[72:73], v[122:123], v[82:83], v[232:233]
	v_lshlrev_b32_e32 v74, 16, v109
	v_and_b32_e32 v75, 0xffff0000, v109
	v_pk_fma_f32 v[72:73], v[130:131], v[84:85], v[72:73]
	v_lshl_add_u64 v[84:85], s[48:49], 0, v[152:153]
	v_pk_fma_f32 v[106:107], v[134:135], v[74:75], v[72:73]
	v_pk_fma_f32 v[72:73], v[112:113], v[92:93], v[234:235]
	v_lshl_add_u64 v[92:93], s[50:51], 0, v[152:153]
	v_pk_fma_f32 v[72:73], v[116:117], v[90:91], v[72:73]
	v_lshlrev_b32_e32 v96, 16, v24
	v_pk_fma_f32 v[104:105], v[124:125], v[76:77], v[72:73]
	v_pk_fma_f32 v[72:73], v[114:115], v[94:95], v[236:237]
	v_lshl_add_u64 v[76:77], s[46:47], 0, v[152:153]
	v_pk_fma_f32 v[72:73], v[118:119], v[86:87], v[72:73]
	v_and_b32_e32 v97, 0xffff0000, v24
	v_pk_fma_f32 v[102:103], v[126:127], v[78:79], v[72:73]
	global_load_dwordx4 v[72:75], v[76:77], off offset:16
	global_load_dwordx4 v[80:83], v[76:77], off
	s_nop 0
	global_load_dwordx4 v[76:79], v[84:85], off offset:16
	global_load_dwordx4 v[88:91], v[84:85], off
	s_nop 0
	global_load_dwordx4 v[84:87], v[92:93], off offset:16
	s_nop 0
	global_load_dwordx4 v[92:95], v[92:93], off
	v_lshlrev_b32_e32 v24, 16, v25
	v_and_b32_e32 v25, 0xffff0000, v25
	v_lshlrev_b32_e32 v108, 16, v48
	v_and_b32_e32 v109, 0xffff0000, v48
	v_lshlrev_b32_e32 v48, 16, v49
	v_and_b32_e32 v49, 0xffff0000, v49
	v_lshlrev_b32_e32 v98, 16, v26
	v_and_b32_e32 v99, 0xffff0000, v26
	v_lshlrev_b32_e32 v114, 16, v44
	v_and_b32_e32 v115, 0xffff0000, v44
	v_lshlrev_b32_e32 v44, 16, v45
	v_and_b32_e32 v45, 0xffff0000, v45
	v_lshlrev_b32_e32 v112, 16, v50
	v_and_b32_e32 v113, 0xffff0000, v50
	v_lshlrev_b32_e32 v26, 16, v27
	v_and_b32_e32 v27, 0xffff0000, v27
	v_lshlrev_b32_e32 v152, 16, v46
	v_and_b32_e32 v153, 0xffff0000, v46
	v_lshlrev_b32_e32 v50, 16, v51
	v_and_b32_e32 v51, 0xffff0000, v51
	v_lshlrev_b32_e32 v46, 16, v47
	v_and_b32_e32 v47, 0xffff0000, v47
	s_waitcnt vmcnt(4)
	v_pk_fma_f32 v[24:25], v[82:83], v[24:25], v[206:207]
	s_waitcnt vmcnt(2)
	v_pk_fma_f32 v[24:25], v[90:91], v[48:49], v[24:25]
	v_pk_fma_f32 v[48:49], v[82:83], v[48:49], v[172:173]
	s_waitcnt vmcnt(0)
	v_pk_fma_f32 v[132:133], v[94:95], v[44:45], v[24:25]
	v_pk_fma_f32 v[24:25], v[72:73], v[98:99], v[208:209]
	v_pk_fma_f32 v[48:49], v[90:91], v[44:45], v[48:49]
	v_pk_fma_f32 v[24:25], v[76:77], v[112:113], v[24:25]
	v_pk_fma_f32 v[96:97], v[80:81], v[96:97], v[204:205]
	v_pk_fma_f32 v[130:131], v[84:85], v[152:153], v[24:25]
	v_pk_fma_f32 v[24:25], v[74:75], v[26:27], v[210:211]
	v_lshlrev_b32_e32 v26, 16, v65
	v_and_b32_e32 v27, 0xffff0000, v65
	v_pk_fma_f32 v[24:25], v[78:79], v[50:51], v[24:25]
	v_pk_fma_f32 v[124:125], v[94:95], v[26:27], v[48:49]
	v_pk_fma_f32 v[48:49], v[72:73], v[112:113], v[174:175]
	v_pk_fma_f32 v[128:129], v[86:87], v[46:47], v[24:25]
	v_lshlrev_b32_e32 v24, 16, v64
	v_and_b32_e32 v25, 0xffff0000, v64
	v_lshlrev_b32_e32 v64, 16, v66
	v_and_b32_e32 v65, 0xffff0000, v66
	v_pk_fma_f32 v[48:49], v[76:77], v[152:153], v[48:49]
	v_lshlrev_b32_e32 v66, 16, v67
	v_pk_fma_f32 v[122:123], v[84:85], v[64:65], v[48:49]
	v_pk_fma_f32 v[48:49], v[74:75], v[50:51], v[180:181]
	v_and_b32_e32 v67, 0xffff0000, v67
	v_pk_fma_f32 v[48:49], v[78:79], v[46:47], v[48:49]
	v_pk_fma_f32 v[44:45], v[82:83], v[44:45], v[184:185]
	v_pk_fma_f32 v[96:97], v[88:89], v[108:109], v[96:97]
	v_pk_fma_f32 v[120:121], v[86:87], v[66:67], v[48:49]
	v_lshlrev_b32_e32 v48, 16, v40
	v_and_b32_e32 v49, 0xffff0000, v40
	v_lshlrev_b32_e32 v40, 16, v41
	v_and_b32_e32 v41, 0xffff0000, v41
	v_pk_fma_f32 v[44:45], v[90:91], v[26:27], v[44:45]
	v_pk_fma_f32 v[134:135], v[92:93], v[114:115], v[96:97]
	v_pk_fma_f32 v[96:97], v[80:81], v[108:109], v[170:171]
	v_pk_fma_f32 v[116:117], v[94:95], v[40:41], v[44:45]
	v_pk_fma_f32 v[44:45], v[72:73], v[152:153], v[186:187]
	v_pk_fma_f32 v[96:97], v[88:89], v[114:115], v[96:97]
	v_lshlrev_b32_e32 v50, 16, v42
	v_and_b32_e32 v51, 0xffff0000, v42
	v_pk_fma_f32 v[44:45], v[76:77], v[64:65], v[44:45]
	v_pk_fma_f32 v[126:127], v[92:93], v[24:25], v[96:97]
	v_pk_fma_f32 v[96:97], v[80:81], v[114:115], v[182:183]
	v_pk_fma_f32 v[114:115], v[84:85], v[50:51], v[44:45]
	v_pk_fma_f32 v[44:45], v[74:75], v[46:47], v[188:189]
	v_lshlrev_b32_e32 v42, 16, v43
	v_and_b32_e32 v43, 0xffff0000, v43
	v_pk_fma_f32 v[96:97], v[88:89], v[24:25], v[96:97]
	v_pk_fma_f32 v[44:45], v[78:79], v[66:67], v[44:45]
	v_pk_fma_f32 v[24:25], v[80:81], v[24:25], v[100:101]
	v_pk_fma_f32 v[112:113], v[86:87], v[42:43], v[44:45]
	v_lshlrev_b32_e32 v44, 16, v60
	v_and_b32_e32 v45, 0xffff0000, v60
	v_pk_fma_f32 v[24:25], v[88:89], v[48:49], v[24:25]
	v_lshlrev_b32_e32 v46, 16, v61
	v_pk_fma_f32 v[108:109], v[92:93], v[44:45], v[24:25]
; __device__ __forceinline__ float silu_f(float v) { return v * __builtin_amdgcn_rcpf(1.0f + __expf(-v)); }
;     __device__ __forceinline__ const char* a(const pg8::Unit& u) const { return (const char*)ws + aoff + (size_t)u.pm * 256 * K_ * 2 + (u.kq < 0 ? 0 : u.kq * (K_ / 4) * 2); }
;     __device__ __forceinline__ const char* b(const pg8::Unit& u) const { return (const char*)ws + boff + (size_t)u.pn * 256 * K_ * 2 + (u.kq < 0 ? 0 : u.kq * (K_ / 4) * 2); }
;     __device__ __forceinline__ const char* a(const pg8::Unit& u) const { return (const char*)ws + WS_A + (size_t)u.pm * 256 * D * 2; }
;     __device__ __forceinline__ const char* b(const pg8::Unit& u) const { return (const char*)ws + boff + (size_t)u.pn * 256 * D * 2; }
;     __device__ __forceinline__ const char* a(const pg8::Unit& u) const { return (const char*)ws + WS_A + (size_t)u.pm * 256 * D * 2; }
;     __device__ __forceinline__ const char* b(const pg8::Unit& u) const { return (const char*)ws + boff + (size_t)u.pn * 256 * D * 2; }
;     __device__ __forceinline__ const char* a(const pg8::Unit& u) const { return (const char*)ws + WS_W1 + (size_t)(u.pm & 1) * 256 * 256 * 2; }
;     __device__ __forceinline__ const char* b(const pg8::Unit& u) const { return (const char*)ws + WS_A + ((size_t)u.pn * 256 * D + (size_t)(u.pm >> 1) * 256) * 2; }
; __device__ __forceinline__ void ffn_conv_phase(Frame& F, int L, int nrows, bool probe_alt = false) {
;     ...
;         FFN_LOAD_ROW(0); FFN_LOAD_ROW(1);
;         f32x2 acc[8][4];
;         { const f32x4* p = (const f32x4*)(cb_ + c0); const f32x4 a = p[0], b = p[1];
; #pragma unroll
;           for (int i = 0; i < 8; ++i) { acc[i][0] = (f32x2){a.x, a.y}; acc[i][1] = (f32x2){a.z, a.w}; acc[i][2] = (f32x2){b.x, b.y}; acc[i][3] = (f32x2){b.z, b.w}; } }
;         FFN_ACC_ROW(0);
;         FFN_LOAD_ROW(2);
; #pragma unroll
;         for (int i = 0; i < 8; ++i) rv[i] = __builtin_nontemporal_load((const u32x4*)(val + (size_t)(rb + tq * 8 + i) * DFF + c0));
;         FFN_ACC_ROW(1);
;         FFN_ACC_ROW(2);
;     ...
; #pragma unroll
;         for (int i = 0; i < 8; ++i) { bf16_t* vp = val + (size_t)(rb + tq * 8 + i) * DFF + c0; float v[8]; unpack8(rv[i], v);
; #pragma unroll
;             for (int c = 0; c < 4; ++c) { v[2 * c] *= silu_f(acc[i][c].x); v[2 * c + 1] *= silu_f(acc[i][c].y); }
;             *(u32x4*)(probe_alt ? vp + (size_t)202 * MiB / 2 : vp) = pack8(v); }
	v_pk_fma_f32 v[24:25], v[82:83], v[26:27], v[190:191]
	v_and_b32_e32 v47, 0xffff0000, v61
	v_pk_fma_f32 v[24:25], v[90:91], v[40:41], v[24:25]
	v_lshlrev_b32_e32 v152, 16, v62
	v_pk_fma_f32 v[100:101], v[94:95], v[46:47], v[24:25]
	v_pk_fma_f32 v[24:25], v[72:73], v[64:65], v[192:193]
	v_and_b32_e32 v153, 0xffff0000, v62
	v_pk_fma_f32 v[24:25], v[76:77], v[50:51], v[24:25]
	v_lshlrev_b32_e32 v170, 16, v63
	v_pk_fma_f32 v[98:99], v[84:85], v[152:153], v[24:25]
	v_pk_fma_f32 v[24:25], v[74:75], v[66:67], v[194:195]
	v_and_b32_e32 v171, 0xffff0000, v63
	v_pk_fma_f32 v[24:25], v[78:79], v[42:43], v[24:25]
	v_pk_fma_f32 v[118:119], v[92:93], v[48:49], v[96:97]
	v_pk_fma_f32 v[96:97], v[86:87], v[170:171], v[24:25]
	v_lshlrev_b32_e32 v24, 16, v36
	v_and_b32_e32 v25, 0xffff0000, v36
	v_lshlrev_b32_e32 v26, 16, v37
	v_and_b32_e32 v27, 0xffff0000, v37
	v_lshlrev_b32_e32 v36, 16, v38
	v_and_b32_e32 v37, 0xffff0000, v38
	v_lshlrev_b32_e32 v172, 16, v39
	v_and_b32_e32 v173, 0xffff0000, v39
	v_pk_fma_f32 v[38:39], v[80:81], v[48:49], v[196:197]
	v_lshlrev_b32_e32 v174, 16, v56
	v_pk_fma_f32 v[38:39], v[88:89], v[44:45], v[38:39]
	v_and_b32_e32 v175, 0xffff0000, v56
	v_pk_fma_f32 v[66:67], v[92:93], v[24:25], v[38:39]
	v_pk_fma_f32 v[38:39], v[82:83], v[40:41], v[198:199]
	v_lshlrev_b32_e32 v56, 16, v57
	v_pk_fma_f32 v[38:39], v[90:91], v[46:47], v[38:39]
	v_and_b32_e32 v57, 0xffff0000, v57
	v_pk_fma_f32 v[64:65], v[94:95], v[26:27], v[38:39]
	v_pk_fma_f32 v[38:39], v[72:73], v[50:51], v[200:201]
	v_lshlrev_b32_e32 v180, 16, v58
	v_pk_fma_f32 v[38:39], v[76:77], v[152:153], v[38:39]
	v_and_b32_e32 v181, 0xffff0000, v58
	v_pk_fma_f32 v[62:63], v[84:85], v[36:37], v[38:39]
	v_pk_fma_f32 v[38:39], v[74:75], v[42:43], v[202:203]
	v_lshlrev_b32_e32 v58, 16, v59
	v_pk_fma_f32 v[38:39], v[78:79], v[170:171], v[38:39]
	v_and_b32_e32 v59, 0xffff0000, v59
	v_pk_fma_f32 v[60:61], v[86:87], v[172:173], v[38:39]
	v_pk_fma_f32 v[38:39], v[80:81], v[44:45], v[168:169]
	s_nop 0
	v_pk_fma_f32 v[38:39], v[88:89], v[24:25], v[38:39]
	v_pk_fma_f32 v[24:25], v[80:81], v[24:25], v[160:161]
	v_pk_fma_f32 v[50:51], v[92:93], v[174:175], v[38:39]
	v_pk_fma_f32 v[38:39], v[82:83], v[46:47], v[166:167]
	v_pk_fma_f32 v[24:25], v[88:89], v[174:175], v[24:25]
	v_pk_fma_f32 v[38:39], v[90:91], v[26:27], v[38:39]
	s_nop 0
	v_pk_fma_f32 v[48:49], v[94:95], v[56:57], v[38:39]
	v_pk_fma_f32 v[38:39], v[72:73], v[152:153], v[164:165]
	v_lshlrev_b32_e32 v152, 16, v32
	v_and_b32_e32 v153, 0xffff0000, v32
	v_pk_fma_f32 v[42:43], v[92:93], v[152:153], v[24:25]
	v_pk_fma_f32 v[24:25], v[82:83], v[26:27], v[158:159]
	v_pk_fma_f32 v[38:39], v[76:77], v[36:37], v[38:39]
	v_lshlrev_b32_e32 v32, 16, v33
	v_and_b32_e32 v33, 0xffff0000, v33
	v_pk_fma_f32 v[24:25], v[90:91], v[56:57], v[24:25]
	v_pk_fma_f32 v[46:47], v[84:85], v[180:181], v[38:39]
	v_pk_fma_f32 v[38:39], v[74:75], v[170:171], v[162:163]
	v_pk_fma_f32 v[40:41], v[94:95], v[32:33], v[24:25]
	v_pk_fma_f32 v[24:25], v[72:73], v[36:37], v[156:157]
	v_pk_fma_f32 v[38:39], v[78:79], v[172:173], v[38:39]
	v_lshlrev_b32_e32 v162, 16, v34
	v_and_b32_e32 v163, 0xffff0000, v34
	v_pk_fma_f32 v[24:25], v[76:77], v[180:181], v[24:25]
	v_pk_fma_f32 v[44:45], v[86:87], v[58:59], v[38:39]
	v_pk_fma_f32 v[38:39], v[84:85], v[162:163], v[24:25]
	v_pk_fma_f32 v[24:25], v[74:75], v[172:173], v[154:155]
	v_lshlrev_b32_e32 v164, 16, v35
	v_and_b32_e32 v165, 0xffff0000, v35
	v_pk_fma_f32 v[24:25], v[78:79], v[58:59], v[24:25]
	v_pk_fma_f32 v[34:35], v[80:81], v[174:175], v[110:111]
	v_pk_fma_f32 v[36:37], v[86:87], v[164:165], v[24:25]
	v_lshlrev_b32_e32 v24, 16, v52
	v_and_b32_e32 v25, 0xffff0000, v52
	v_pk_fma_f32 v[34:35], v[88:89], v[152:153], v[34:35]
	v_lshlrev_b32_e32 v26, 16, v53
	v_pk_fma_f32 v[34:35], v[92:93], v[24:25], v[34:35]
	v_pk_fma_f32 v[24:25], v[82:83], v[56:57], v[106:107]
	v_and_b32_e32 v27, 0xffff0000, v53
	v_pk_fma_f32 v[24:25], v[90:91], v[32:33], v[24:25]
	v_lshlrev_b32_e32 v52, 16, v54
	v_pk_fma_f32 v[32:33], v[94:95], v[26:27], v[24:25]
	v_pk_fma_f32 v[24:25], v[72:73], v[180:181], v[104:105]
	v_and_b32_e32 v53, 0xffff0000, v54
	v_pk_fma_f32 v[24:25], v[76:77], v[162:163], v[24:25]
	v_lshlrev_b32_e32 v54, 16, v55
	v_pk_fma_f32 v[26:27], v[84:85], v[52:53], v[24:25]
	v_mul_f32_e32 v52, 0xbfb8aa3b, v134
	v_mul_f32_e32 v53, 0xbfb8aa3b, v135
	v_exp_f32_e32 v52, v52
	v_exp_f32_e32 v53, v53
	v_pk_fma_f32 v[24:25], v[74:75], v[58:59], v[102:103]
	v_and_b32_e32 v55, 0xffff0000, v55
	v_add_f32_e32 v52, 1.0, v52
	v_add_f32_e32 v53, 1.0, v53
	v_rcp_f32_e32 v52, v52
	v_rcp_f32_e32 v53, v53
	v_pk_fma_f32 v[24:25], v[78:79], v[164:165], v[24:25]
	v_lshlrev_b32_e32 v56, 16, v69
	v_pk_fma_f32 v[24:25], v[86:87], v[54:55], v[24:25]
	v_lshlrev_b32_e32 v54, 16, v68
	v_and_b32_e32 v55, 0xffff0000, v68
	v_pk_mul_f32 v[52:53], v[134:135], v[52:53]
	v_and_b32_e32 v57, 0xffff0000, v69
	v_pk_mul_f32 v[52:53], v[52:53], v[54:55]
	v_mul_f32_e32 v54, 0xbfb8aa3b, v132
	v_mul_f32_e32 v55, 0xbfb8aa3b, v133
	v_exp_f32_e32 v54, v54
	v_exp_f32_e32 v55, v55
	v_lshlrev_b32_e32 v58, 16, v70
	v_and_b32_e32 v59, 0xffff0000, v70
	v_add_f32_e32 v54, 1.0, v54
	v_add_f32_e32 v55, 1.0, v55
	v_rcp_f32_e32 v54, v54
	v_rcp_f32_e32 v55, v55
	v_lshlrev_b32_e32 v68, 16, v71
	v_and_b32_e32 v69, 0xffff0000, v71
	v_cvt_pk_bf16_f32 v52, v52, v53
	v_pk_mul_f32 v[54:55], v[132:133], v[54:55]
	s_nop 0
	v_pk_mul_f32 v[54:55], v[54:55], v[56:57]
	v_mul_f32_e32 v56, 0xbfb8aa3b, v130
	v_mul_f32_e32 v57, 0xbfb8aa3b, v131
	v_exp_f32_e32 v56, v56
	v_exp_f32_e32 v57, v57
	v_cvt_pk_bf16_f32 v53, v54, v55
	v_add_f32_e32 v56, 1.0, v56
	v_add_f32_e32 v57, 1.0, v57
	v_rcp_f32_e32 v56, v56
; __device__ __forceinline__ float silu_f(float v) { return v * __builtin_amdgcn_rcpf(1.0f + __expf(-v)); }
; __device__ __forceinline__ u32x4 pack8(const float (&f)[8]) { u32x4 w; w.x = cvt_pk_bf16(f[0], f[1]); w.y = cvt_pk_bf16(f[2], f[3]); w.z = cvt_pk_bf16(f[4], f[5]); w.w = cvt_pk_bf16(f[6], f[7]); return w; }
; __device__ __forceinline__ void ffn_conv_phase(Frame& F, int L, int nrows, bool probe_alt = false) {
;     ...
; #pragma unroll
;         for (int i = 0; i < 8; ++i) { bf16_t* vp = val + (size_t)(rb + tq * 8 + i) * DFF + c0; float v[8]; unpack8(rv[i], v);
; #pragma unroll
;             for (int c = 0; c < 4; ++c) { v[2 * c] *= silu_f(acc[i][c].x); v[2 * c + 1] *= silu_f(acc[i][c].y); }
;             *(u32x4*)(probe_alt ? vp + (size_t)202 * MiB / 2 : vp) = pack8(v); }
	v_rcp_f32_e32 v57, v57
	s_nop 0
	v_pk_mul_f32 v[56:57], v[130:131], v[56:57]
	s_nop 0
	v_pk_mul_f32 v[56:57], v[56:57], v[58:59]
	v_mul_f32_e32 v58, 0xbfb8aa3b, v128
	v_mul_f32_e32 v59, 0xbfb8aa3b, v129
	v_exp_f32_e32 v58, v58
	v_exp_f32_e32 v59, v59
	v_cvt_pk_bf16_f32 v54, v56, v57
	v_lshlrev_b32_e32 v56, 16, v30
	v_add_f32_e32 v58, 1.0, v58
	v_add_f32_e32 v59, 1.0, v59
	v_rcp_f32_e32 v58, v58
	v_rcp_f32_e32 v59, v59
	v_and_b32_e32 v57, 0xffff0000, v30
	v_lshlrev_b32_e32 v30, 16, v31
	v_and_b32_e32 v31, 0xffff0000, v31
	v_pk_mul_f32 v[58:59], v[128:129], v[58:59]
	s_nop 0
	v_pk_mul_f32 v[58:59], v[58:59], v[68:69]
	s_nop 0
	v_cvt_pk_bf16_f32 v55, v58, v59
	global_store_dwordx4 v[150:151], v[52:55], off
	s_nop 1
	v_mul_f32_e32 v52, 0xbfb8aa3b, v126
	v_mul_f32_e32 v53, 0xbfb8aa3b, v127
	v_exp_f32_e32 v52, v52
	v_exp_f32_e32 v53, v53
	v_lshlrev_b32_e32 v54, 16, v28
	v_and_b32_e32 v55, 0xffff0000, v28
	v_add_f32_e32 v52, 1.0, v52
	v_add_f32_e32 v53, 1.0, v53
	v_mul_f32_e32 v28, 0xbfb8aa3b, v124
	v_rcp_f32_e32 v52, v52
	v_rcp_f32_e32 v53, v53
	v_exp_f32_e32 v28, v28
	v_pk_mul_f32 v[52:53], v[126:127], v[52:53]
	v_add_f32_e32 v28, 1.0, v28
	v_pk_mul_f32 v[52:53], v[52:53], v[54:55]
	v_rcp_f32_e32 v54, v28
	v_mul_f32_e32 v28, 0xbfb8aa3b, v125
	v_exp_f32_e32 v28, v28
	s_nop 0
	v_add_f32_e32 v28, 1.0, v28
	v_rcp_f32_e32 v55, v28
	v_lshlrev_b32_e32 v28, 16, v29
	v_and_b32_e32 v29, 0xffff0000, v29
	v_pk_mul_f32 v[54:55], v[124:125], v[54:55]
	s_nop 0
	v_pk_mul_f32 v[54:55], v[54:55], v[28:29]
	v_mul_f32_e32 v28, 0xbfb8aa3b, v122
	v_mul_f32_e32 v29, 0xbfb8aa3b, v123
	v_exp_f32_e32 v28, v28
	v_exp_f32_e32 v29, v29
	v_add_f32_e32 v28, 1.0, v28
	v_add_f32_e32 v29, 1.0, v29
	v_rcp_f32_e32 v28, v28
	v_rcp_f32_e32 v29, v29
	s_nop 0
	v_pk_mul_f32 v[28:29], v[122:123], v[28:29]
	s_nop 0
	v_pk_mul_f32 v[56:57], v[28:29], v[56:57]
	v_mul_f32_e32 v28, 0xbfb8aa3b, v120
	v_mul_f32_e32 v29, 0xbfb8aa3b, v121
	v_exp_f32_e32 v28, v28
	v_exp_f32_e32 v29, v29
	v_add_f32_e32 v28, 1.0, v28
	v_add_f32_e32 v29, 1.0, v29
	v_rcp_f32_e32 v28, v28
	v_rcp_f32_e32 v29, v29
	s_nop 0
	v_pk_mul_f32 v[28:29], v[120:121], v[28:29]
	s_nop 0
	v_pk_mul_f32 v[58:59], v[28:29], v[30:31]
	v_cvt_pk_bf16_f32 v28, v52, v53
	v_cvt_pk_bf16_f32 v29, v54, v55
	v_cvt_pk_bf16_f32 v30, v56, v57
	v_cvt_pk_bf16_f32 v31, v58, v59
	global_store_dwordx4 v[148:149], v[28:31], off
	v_lshlrev_b32_e32 v52, 16, v22
	v_and_b32_e32 v53, 0xffff0000, v22
	v_mul_f32_e32 v28, 0xbfb8aa3b, v118
	v_mul_f32_e32 v29, 0xbfb8aa3b, v119
	v_exp_f32_e32 v28, v28
	v_exp_f32_e32 v29, v29
	v_lshlrev_b32_e32 v30, 16, v20
	v_and_b32_e32 v31, 0xffff0000, v20
	v_add_f32_e32 v28, 1.0, v28
	v_add_f32_e32 v29, 1.0, v29
	v_mul_f32_e32 v20, 0xbfb8aa3b, v116
	v_rcp_f32_e32 v28, v28
	v_rcp_f32_e32 v29, v29
	v_exp_f32_e32 v20, v20
	v_lshlrev_b32_e32 v22, 16, v23
	v_and_b32_e32 v23, 0xffff0000, v23
	v_pk_mul_f32 v[28:29], v[118:119], v[28:29]
	v_add_f32_e32 v20, 1.0, v20
	v_pk_mul_f32 v[28:29], v[28:29], v[30:31]
	v_rcp_f32_e32 v30, v20
	v_mul_f32_e32 v20, 0xbfb8aa3b, v117
	v_exp_f32_e32 v20, v20
	s_nop 0
	v_add_f32_e32 v20, 1.0, v20
	v_rcp_f32_e32 v31, v20
	v_lshlrev_b32_e32 v20, 16, v21
	v_and_b32_e32 v21, 0xffff0000, v21
	v_pk_mul_f32 v[30:31], v[116:117], v[30:31]
	s_nop 0
	v_pk_mul_f32 v[30:31], v[30:31], v[20:21]
	v_mul_f32_e32 v20, 0xbfb8aa3b, v114
	v_mul_f32_e32 v21, 0xbfb8aa3b, v115
	v_exp_f32_e32 v20, v20
	v_exp_f32_e32 v21, v21
	v_add_f32_e32 v20, 1.0, v20
	v_add_f32_e32 v21, 1.0, v21
	v_rcp_f32_e32 v20, v20
	v_rcp_f32_e32 v21, v21
	s_nop 0
	v_pk_mul_f32 v[20:21], v[114:115], v[20:21]
	s_nop 0
	v_pk_mul_f32 v[52:53], v[20:21], v[52:53]
	v_mul_f32_e32 v20, 0xbfb8aa3b, v112
	v_mul_f32_e32 v21, 0xbfb8aa3b, v113
	v_exp_f32_e32 v20, v20
	v_exp_f32_e32 v21, v21
	v_add_f32_e32 v20, 1.0, v20
	v_add_f32_e32 v21, 1.0, v21
	v_rcp_f32_e32 v20, v20
	v_rcp_f32_e32 v21, v21
	s_nop 0
	v_pk_mul_f32 v[20:21], v[112:113], v[20:21]
	s_nop 0
	v_pk_mul_f32 v[54:55], v[20:21], v[22:23]
	v_cvt_pk_bf16_f32 v20, v28, v29
	v_cvt_pk_bf16_f32 v21, v30, v31
	v_cvt_pk_bf16_f32 v22, v52, v53
	v_cvt_pk_bf16_f32 v23, v54, v55
	global_store_dwordx4 v[146:147], v[20:23], off
	v_lshlrev_b32_e32 v28, 16, v18
	v_and_b32_e32 v29, 0xffff0000, v18
	v_mul_f32_e32 v20, 0xbfb8aa3b, v108
	v_mul_f32_e32 v21, 0xbfb8aa3b, v109
	v_exp_f32_e32 v20, v20
	v_exp_f32_e32 v21, v21
	v_lshlrev_b32_e32 v22, 16, v16
	v_and_b32_e32 v23, 0xffff0000, v16
	v_add_f32_e32 v20, 1.0, v20
	v_add_f32_e32 v21, 1.0, v21
	v_mul_f32_e32 v16, 0xbfb8aa3b, v100
	v_rcp_f32_e32 v20, v20
	v_rcp_f32_e32 v21, v21
	v_exp_f32_e32 v16, v16
	v_lshlrev_b32_e32 v18, 16, v19
	v_and_b32_e32 v19, 0xffff0000, v19
	v_pk_mul_f32 v[20:21], v[108:109], v[20:21]
	v_add_f32_e32 v16, 1.0, v16
	v_pk_mul_f32 v[20:21], v[20:21], v[22:23]
	v_rcp_f32_e32 v22, v16
	v_mul_f32_e32 v16, 0xbfb8aa3b, v101
	v_exp_f32_e32 v16, v16
	s_nop 0
	v_add_f32_e32 v16, 1.0, v16
	v_rcp_f32_e32 v23, v16
	v_lshlrev_b32_e32 v16, 16, v17
	v_and_b32_e32 v17, 0xffff0000, v17
	v_pk_mul_f32 v[22:23], v[100:101], v[22:23]
	s_nop 0
	v_pk_mul_f32 v[22:23], v[22:23], v[16:17]
	v_mul_f32_e32 v16, 0xbfb8aa3b, v98
	v_mul_f32_e32 v17, 0xbfb8aa3b, v99
	v_exp_f32_e32 v16, v16
	v_exp_f32_e32 v17, v17
	v_add_f32_e32 v16, 1.0, v16
	v_add_f32_e32 v17, 1.0, v17
	v_rcp_f32_e32 v16, v16
	v_rcp_f32_e32 v17, v17
	s_nop 0
	v_pk_mul_f32 v[16:17], v[98:99], v[16:17]
	s_nop 0
	v_pk_mul_f32 v[28:29], v[16:17], v[28:29]
	v_mul_f32_e32 v16, 0xbfb8aa3b, v96
	v_mul_f32_e32 v17, 0xbfb8aa3b, v97
	v_exp_f32_e32 v16, v16
	v_exp_f32_e32 v17, v17
	v_add_f32_e32 v16, 1.0, v16
	v_add_f32_e32 v17, 1.0, v17
	v_rcp_f32_e32 v16, v16
	v_rcp_f32_e32 v17, v17
	s_nop 0
	v_pk_mul_f32 v[16:17], v[96:97], v[16:17]
; __device__ __forceinline__ float silu_f(float v) { return v * __builtin_amdgcn_rcpf(1.0f + __expf(-v)); }
; __device__ __forceinline__ u32x4 pack8(const float (&f)[8]) { u32x4 w; w.x = cvt_pk_bf16(f[0], f[1]); w.y = cvt_pk_bf16(f[2], f[3]); w.z = cvt_pk_bf16(f[4], f[5]); w.w = cvt_pk_bf16(f[6], f[7]); return w; }
; __device__ __forceinline__ void ffn_conv_phase(Frame& F, int L, int nrows, bool probe_alt = false) {
;     ...
; #pragma unroll
;         for (int i = 0; i < 8; ++i) { bf16_t* vp = val + (size_t)(rb + tq * 8 + i) * DFF + c0; float v[8]; unpack8(rv[i], v);
; #pragma unroll
;             for (int c = 0; c < 4; ++c) { v[2 * c] *= silu_f(acc[i][c].x); v[2 * c + 1] *= silu_f(acc[i][c].y); }
;             *(u32x4*)(probe_alt ? vp + (size_t)202 * MiB / 2 : vp) = pack8(v); }
;     }
	s_nop 0
	v_pk_mul_f32 v[30:31], v[16:17], v[18:19]
	v_cvt_pk_bf16_f32 v16, v20, v21
	v_cvt_pk_bf16_f32 v17, v22, v23
	v_cvt_pk_bf16_f32 v18, v28, v29
	v_cvt_pk_bf16_f32 v19, v30, v31
	global_store_dwordx4 v[144:145], v[16:19], off
	v_lshlrev_b32_e32 v20, 16, v14
	v_and_b32_e32 v21, 0xffff0000, v14
	v_mul_f32_e32 v16, 0xbfb8aa3b, v66
	v_mul_f32_e32 v17, 0xbfb8aa3b, v67
	v_exp_f32_e32 v16, v16
	v_exp_f32_e32 v17, v17
	v_lshlrev_b32_e32 v18, 16, v12
	v_and_b32_e32 v19, 0xffff0000, v12
	v_add_f32_e32 v16, 1.0, v16
	v_add_f32_e32 v17, 1.0, v17
	v_mul_f32_e32 v12, 0xbfb8aa3b, v64
	v_rcp_f32_e32 v16, v16
	v_rcp_f32_e32 v17, v17
	v_exp_f32_e32 v12, v12
	v_lshlrev_b32_e32 v14, 16, v15
	v_and_b32_e32 v15, 0xffff0000, v15
	v_pk_mul_f32 v[16:17], v[66:67], v[16:17]
	v_add_f32_e32 v12, 1.0, v12
	v_pk_mul_f32 v[16:17], v[16:17], v[18:19]
	v_rcp_f32_e32 v18, v12
	v_mul_f32_e32 v12, 0xbfb8aa3b, v65
	v_exp_f32_e32 v12, v12
	s_nop 0
	v_add_f32_e32 v12, 1.0, v12
	v_rcp_f32_e32 v19, v12
	v_lshlrev_b32_e32 v12, 16, v13
	v_and_b32_e32 v13, 0xffff0000, v13
	v_pk_mul_f32 v[18:19], v[64:65], v[18:19]
	s_nop 0
	v_pk_mul_f32 v[18:19], v[18:19], v[12:13]
	v_mul_f32_e32 v12, 0xbfb8aa3b, v62
	v_mul_f32_e32 v13, 0xbfb8aa3b, v63
	v_exp_f32_e32 v12, v12
	v_exp_f32_e32 v13, v13
	v_add_f32_e32 v12, 1.0, v12
	v_add_f32_e32 v13, 1.0, v13
	v_rcp_f32_e32 v12, v12
	v_rcp_f32_e32 v13, v13
	s_nop 0
	v_pk_mul_f32 v[12:13], v[62:63], v[12:13]
	s_nop 0
	v_pk_mul_f32 v[20:21], v[12:13], v[20:21]
	v_mul_f32_e32 v12, 0xbfb8aa3b, v60
	v_mul_f32_e32 v13, 0xbfb8aa3b, v61
	v_exp_f32_e32 v12, v12
	v_exp_f32_e32 v13, v13
	v_add_f32_e32 v12, 1.0, v12
	v_add_f32_e32 v13, 1.0, v13
	v_rcp_f32_e32 v12, v12
	v_rcp_f32_e32 v13, v13
	s_nop 0
	v_pk_mul_f32 v[12:13], v[60:61], v[12:13]
	s_nop 0
	v_pk_mul_f32 v[22:23], v[12:13], v[14:15]
	v_cvt_pk_bf16_f32 v12, v16, v17
	v_cvt_pk_bf16_f32 v13, v18, v19
	v_cvt_pk_bf16_f32 v14, v20, v21
	v_cvt_pk_bf16_f32 v15, v22, v23
	global_store_dwordx4 v[142:143], v[12:15], off
	v_lshlrev_b32_e32 v16, 16, v10
	v_and_b32_e32 v17, 0xffff0000, v10
	v_mul_f32_e32 v12, 0xbfb8aa3b, v50
	v_mul_f32_e32 v13, 0xbfb8aa3b, v51
	v_exp_f32_e32 v12, v12
	v_exp_f32_e32 v13, v13
	v_lshlrev_b32_e32 v14, 16, v8
	v_and_b32_e32 v15, 0xffff0000, v8
	v_add_f32_e32 v12, 1.0, v12
	v_add_f32_e32 v13, 1.0, v13
	v_mul_f32_e32 v8, 0xbfb8aa3b, v48
	v_rcp_f32_e32 v12, v12
	v_rcp_f32_e32 v13, v13
	v_exp_f32_e32 v8, v8
	v_lshlrev_b32_e32 v10, 16, v11
	v_and_b32_e32 v11, 0xffff0000, v11
	v_pk_mul_f32 v[12:13], v[50:51], v[12:13]
	v_add_f32_e32 v8, 1.0, v8
	v_pk_mul_f32 v[12:13], v[12:13], v[14:15]
	v_rcp_f32_e32 v14, v8
	v_mul_f32_e32 v8, 0xbfb8aa3b, v49
	v_exp_f32_e32 v8, v8
	s_nop 0
	v_add_f32_e32 v8, 1.0, v8
	v_rcp_f32_e32 v15, v8
	v_lshlrev_b32_e32 v8, 16, v9
	v_and_b32_e32 v9, 0xffff0000, v9
	v_pk_mul_f32 v[14:15], v[48:49], v[14:15]
	s_nop 0
	v_pk_mul_f32 v[14:15], v[14:15], v[8:9]
	v_mul_f32_e32 v8, 0xbfb8aa3b, v46
	v_mul_f32_e32 v9, 0xbfb8aa3b, v47
	v_exp_f32_e32 v8, v8
	v_exp_f32_e32 v9, v9
	v_add_f32_e32 v8, 1.0, v8
	v_add_f32_e32 v9, 1.0, v9
	v_rcp_f32_e32 v8, v8
	v_rcp_f32_e32 v9, v9
	s_nop 0
	v_pk_mul_f32 v[8:9], v[46:47], v[8:9]
	s_nop 0
	v_pk_mul_f32 v[16:17], v[8:9], v[16:17]
	v_mul_f32_e32 v8, 0xbfb8aa3b, v44
	v_mul_f32_e32 v9, 0xbfb8aa3b, v45
	v_exp_f32_e32 v8, v8
	v_exp_f32_e32 v9, v9
	v_add_f32_e32 v8, 1.0, v8
	v_add_f32_e32 v9, 1.0, v9
	v_rcp_f32_e32 v8, v8
	v_rcp_f32_e32 v9, v9
	s_nop 0
	v_pk_mul_f32 v[8:9], v[44:45], v[8:9]
	s_nop 0
	v_pk_mul_f32 v[18:19], v[8:9], v[10:11]
	v_cvt_pk_bf16_f32 v8, v12, v13
	v_cvt_pk_bf16_f32 v9, v14, v15
	v_cvt_pk_bf16_f32 v10, v16, v17
	v_cvt_pk_bf16_f32 v11, v18, v19
	global_store_dwordx4 v[140:141], v[8:11], off
	v_lshlrev_b32_e32 v12, 16, v6
	v_and_b32_e32 v13, 0xffff0000, v6
	v_mul_f32_e32 v8, 0xbfb8aa3b, v42
	v_mul_f32_e32 v9, 0xbfb8aa3b, v43
	v_exp_f32_e32 v8, v8
	v_exp_f32_e32 v9, v9
	v_lshlrev_b32_e32 v10, 16, v4
	v_and_b32_e32 v11, 0xffff0000, v4
	v_add_f32_e32 v8, 1.0, v8
	v_add_f32_e32 v9, 1.0, v9
	v_mul_f32_e32 v4, 0xbfb8aa3b, v40
	v_rcp_f32_e32 v8, v8
	v_rcp_f32_e32 v9, v9
	v_exp_f32_e32 v4, v4
	v_lshlrev_b32_e32 v6, 16, v7
	v_and_b32_e32 v7, 0xffff0000, v7
	v_pk_mul_f32 v[8:9], v[42:43], v[8:9]
	v_add_f32_e32 v4, 1.0, v4
	v_pk_mul_f32 v[8:9], v[8:9], v[10:11]
	v_rcp_f32_e32 v10, v4
	v_mul_f32_e32 v4, 0xbfb8aa3b, v41
	v_exp_f32_e32 v4, v4
	s_nop 0
	v_add_f32_e32 v4, 1.0, v4
	v_rcp_f32_e32 v11, v4
	v_lshlrev_b32_e32 v4, 16, v5
	v_and_b32_e32 v5, 0xffff0000, v5
	v_pk_mul_f32 v[10:11], v[40:41], v[10:11]
	s_nop 0
	v_pk_mul_f32 v[10:11], v[10:11], v[4:5]
	v_mul_f32_e32 v4, 0xbfb8aa3b, v38
	v_mul_f32_e32 v5, 0xbfb8aa3b, v39
	v_exp_f32_e32 v4, v4
	v_exp_f32_e32 v5, v5
	v_add_f32_e32 v4, 1.0, v4
	v_add_f32_e32 v5, 1.0, v5
	v_rcp_f32_e32 v4, v4
	v_rcp_f32_e32 v5, v5
	s_nop 0
	v_pk_mul_f32 v[4:5], v[38:39], v[4:5]
	s_nop 0
	v_pk_mul_f32 v[12:13], v[4:5], v[12:13]
	v_mul_f32_e32 v4, 0xbfb8aa3b, v36
	v_mul_f32_e32 v5, 0xbfb8aa3b, v37
	v_exp_f32_e32 v4, v4
	v_exp_f32_e32 v5, v5
	v_add_f32_e32 v4, 1.0, v4
	v_add_f32_e32 v5, 1.0, v5
	v_rcp_f32_e32 v4, v4
	v_rcp_f32_e32 v5, v5
	s_nop 0
	v_pk_mul_f32 v[4:5], v[36:37], v[4:5]
	s_nop 0
	v_pk_mul_f32 v[14:15], v[4:5], v[6:7]
	v_cvt_pk_bf16_f32 v4, v8, v9
	v_cvt_pk_bf16_f32 v5, v10, v11
	v_cvt_pk_bf16_f32 v6, v12, v13
	v_cvt_pk_bf16_f32 v7, v14, v15
	global_store_dwordx4 v[138:139], v[4:7], off
	v_lshlrev_b32_e32 v8, 16, v2
	v_and_b32_e32 v9, 0xffff0000, v2
	v_mul_f32_e32 v4, 0xbfb8aa3b, v34
	v_mul_f32_e32 v5, 0xbfb8aa3b, v35
	v_exp_f32_e32 v4, v4
	v_exp_f32_e32 v5, v5
	v_lshlrev_b32_e32 v6, 16, v0
	v_and_b32_e32 v7, 0xffff0000, v0
	v_add_f32_e32 v4, 1.0, v4
	v_add_f32_e32 v5, 1.0, v5
	v_mul_f32_e32 v0, 0xbfb8aa3b, v32
	v_rcp_f32_e32 v4, v4
	v_rcp_f32_e32 v5, v5
	v_exp_f32_e32 v0, v0
	v_lshlrev_b32_e32 v2, 16, v3
	v_and_b32_e32 v3, 0xffff0000, v3
	v_pk_mul_f32 v[4:5], v[34:35], v[4:5]
	v_add_f32_e32 v0, 1.0, v0
	v_pk_mul_f32 v[4:5], v[4:5], v[6:7]
	v_rcp_f32_e32 v6, v0
	v_mul_f32_e32 v0, 0xbfb8aa3b, v33
	v_exp_f32_e32 v0, v0
	s_nop 0
	v_add_f32_e32 v0, 1.0, v0
	v_rcp_f32_e32 v7, v0
	v_lshlrev_b32_e32 v0, 16, v1
	v_and_b32_e32 v1, 0xffff0000, v1
	v_pk_mul_f32 v[6:7], v[32:33], v[6:7]
	s_nop 0
	v_pk_mul_f32 v[6:7], v[6:7], v[0:1]
	v_mul_f32_e32 v0, 0xbfb8aa3b, v26
	v_mul_f32_e32 v1, 0xbfb8aa3b, v27
	v_exp_f32_e32 v0, v0
	v_exp_f32_e32 v1, v1
	v_add_f32_e32 v0, 1.0, v0
	v_add_f32_e32 v1, 1.0, v1
	v_rcp_f32_e32 v0, v0
	v_rcp_f32_e32 v1, v1
	s_nop 0
	v_pk_mul_f32 v[0:1], v[26:27], v[0:1]
	s_nop 0
	v_pk_mul_f32 v[8:9], v[0:1], v[8:9]
	v_mul_f32_e32 v0, 0xbfb8aa3b, v24
	v_mul_f32_e32 v1, 0xbfb8aa3b, v25
	v_exp_f32_e32 v0, v0
	v_exp_f32_e32 v1, v1
	v_add_f32_e32 v0, 1.0, v0
	v_add_f32_e32 v1, 1.0, v1
	v_rcp_f32_e32 v0, v0
	v_rcp_f32_e32 v1, v1
	s_nop 0
	v_pk_mul_f32 v[0:1], v[24:25], v[0:1]
	s_nop 0
	v_pk_mul_f32 v[10:11], v[0:1], v[2:3]
	v_cvt_pk_bf16_f32 v0, v4, v5
	v_cvt_pk_bf16_f32 v1, v6, v7
	v_cvt_pk_bf16_f32 v2, v8, v9
	v_cvt_pk_bf16_f32 v3, v10, v11
	global_store_dwordx4 v[136:137], v[0:3], off
	s_cbranch_scc0 .LBB0_1266
; __device__ __forceinline__ int fresh_lane() { int l; asm volatile("v_mbcnt_lo_u32_b32 %0, -1, 0\n\tv_mbcnt_hi_u32_b32 %0, -1, %0" : "=v"(l)); return l; }
; __device__ __forceinline__ void ffn_conv_phase(Frame& F, int L, int nrows, bool probe_alt = false) {
;     ...
;     for (int job = gw; job < NTB * NCB; job += NGW) {
;         const int lane = fresh_lane(), cq = lane & 7, tq = lane >> 3;
;         const int cb = job / NTB, tb = job % NTB;
;         const int rb = tb * 64, c0 = cb * 64 + cq * 8;
;         const bool lat = rb < MLAT;
;         const int gr = lat ? (tb & 31) : 0, base = lat ? (rb - gr * 64) : (MLAT + (((rb - MLAT) >> 8) << 8)), q = lat ? 0 : (((rb - MLAT) >> 6) & 3);
;         u32x4 raw[3][10], rv[8];
.LBB0_1206:
	s_sub_i32 s100, s7, s77
	s_add_i32 s100, s100, -1
	s_lshl_b32 s101, s100, 6
	s_or_b32 s101, s101, 7
	s_abs_i32 s5, s100
	s_mul_hi_u32 s17, s5, s73
	s_mul_i32 s27, s17, s14
	s_ashr_i32 s4, s100, 31
	s_sub_i32 s5, s5, s27
	s_xor_b32 s4, s4, s15
	s_add_i32 s27, s17, 1
	s_sub_i32 s36, s5, s14
	s_cmp_ge_u32 s5, s14
	s_cselect_b32 s17, s27, s17
	s_cselect_b32 s5, s36, s5
	s_add_i32 s27, s17, 1
	s_cmp_ge_u32 s5, s14
	s_cselect_b32 s5, s27, s17
	s_xor_b32 s5, s5, s4
	s_sub_i32 s78, s5, s4
	s_mul_i32 s4, s78, s6
	s_sub_i32 s4, s100, s4
	s_mul_i32 s5, s76, s78
	s_min_i32 s4, s4, 0x100
	s_add_i32 s17, s100, s5
	s_mul_i32 s5, s75, s78
	s_and_b32 s4, s4, 31
	s_add_i32 s5, s101, s5
	s_min_i32 s27, s17, 0x100
	s_sub_i32 s4, s17, s4
	s_add_i32 s5, s5, -7
	s_and_b32 s79, s27, 31
	s_lshl_b32 s27, s4, 6
	s_max_i32 s4, s17, 0x100
	s_and_b32 s40, s5, 0x7fffff00
	s_and_b32 s87, s4, 3
	s_cmp_lg_u32 s79, 0
	s_cselect_b64 s[4:5], -1, 0
	s_lshl_b32 s80, s79, 6
	s_sub_i32 s41, s80, 64
	s_lshl_b32 s81, s87, 6
	s_cmpk_lt_i32 s17, 0x100
	v_mbcnt_lo_u32_b32 v24, -1, 0
	v_mbcnt_hi_u32_b32 v24, -1, v24
	s_cselect_b64 s[36:37], -1, 0
	v_lshlrev_b32_e32 v0, 3, v24
	v_and_b32_e32 v0, 56, v0
	s_and_b64 s[38:39], s[36:37], exec
	v_and_b32_e32 v176, -8, v24
	v_lshl_or_b32 v154, s78, 6, v0
	s_cselect_b32 s86, s27, s40
	s_cselect_b32 s17, s41, s81
	s_and_b64 s[94:95], s[36:37], s[4:5]
	v_add_u32_e32 v32, -1, v176
	v_readlane_b32 s4, v252, 62
	v_ashrrev_i32_e32 v155, 31, v154
	v_readlane_b32 s5, v252, 63
	v_cmp_gt_u32_e64 s[38:39], 64, v32
	s_add_i32 s93, s86, s17
	v_lshl_add_u64 v[156:157], v[154:155], 1, s[4:5]
	s_and_b64 s[40:41], s[94:95], s[38:39]
	v_mov_b32_e32 v0, 0
	v_mov_b32_e32 v12, 0
	v_mov_b32_e32 v13, 0
	v_mov_b32_e32 v14, 0
	v_mov_b32_e32 v15, 0
	s_and_saveexec_b64 s[4:5], s[40:41]
	s_cbranch_execz .LBB0_1208
	v_or_b32_e32 v1, s93, v32
	v_mad_i64_i32 v[2:3], s[40:41], v1, s89, v[156:157]
	global_load_dwordx4 v[12:15], v[2:3], off
